# speedup vs baseline: 1.0382x; 1.0003x over previous
; __device__ __forceinline__ void phase_attn(CParams& p, int slot, char* smem) {
;   int* misc = reinterpret_cast<int*>(smem + MISC_OFF);
;   for (;;) {
;     if (threadIdx.x == 0) misc[0] = (int)atomicAdd(p.ctr + 16 + slot, 1u);
.LBB0_317:
	s_and_b64 vcc, exec, s[2:3]
	s_cbranch_vccz .LBB0_378
	v_writelane_b32 v255, 0, 23
	v_readlane_b32 s2, v254, 63
	v_readlane_b32 s3, v255, 0
	s_waitcnt lgkmcnt(0)
	s_nop 0
	v_cndmask_b32_e64 v0, 0, 1, s[2:3]
	s_load_dwordx2 s[2:3], s[96:97], 0x90
	s_load_dwordx2 s[62:63], s[96:97], 0xa8
	s_load_dwordx4 s[52:55], s[96:97], 0x130
	v_lshlrev_b32_e32 v0, 2, v0
	s_waitcnt lgkmcnt(0)
	v_lshl_add_u64 v[152:153], s[2:3], 0, v[0:1]
	s_branch .LBB0_321

; __device__ __forceinline__ void phase_attn(CParams& p, int slot, char* smem) {
;   int* misc = reinterpret_cast<int*>(smem + MISC_OFF);
;   for (;;) {
;     if (threadIdx.x == 0) misc[0] = (int)atomicAdd(p.ctr + 16 + slot, 1u);
;     __syncthreads();
;     const int item = misc[0];
;     __syncthreads();
;     if (item >= 1056) break;
;     if (item < 528) {
;       const int qt = 32 - (item >> 4), bh = item & 15;
;       attn_item<0>(p.Q, p.Kn, p.Kr, p.VmT, p.hb, bh >> 3, bh & 7, qt, smem);
;     } else {
;       const int it = item - 528;
;       const int qt = 32 - (it >> 4), bh = it & 15;
;       attn_item<1>(p.Qsb, p.Ksb, p.Kr, p.VsbT, p.hb, bh >> 3, bh & 7, qt, smem);
;     }
.LBB0_321:
	s_mov_b64 s[2:3], exec
	v_readlane_b32 s6, v254, 7
	v_readlane_b32 s7, v254, 8
	s_and_b64 s[6:7], s[2:3], s[6:7]
	s_mov_b64 exec, s[6:7]
	s_cbranch_execz .LBB0_325
	s_waitcnt vmcnt(0) lgkmcnt(0)
.Lq_retry:
	v_readlane_b32 s8, v255, 23
	s_nop 0
	s_cmp_ge_u32 s8, 8
	s_cbranch_scc1 .Lq_done_all
	s_getreg_b32 s9, hwreg(HW_REG_XCC_ID, 0, 4)
	s_add_u32 s9, s9, s8
	s_and_b32 s9, s9, 7
	s_lshl_b32 s6, s9, 3
	v_mov_b32_e32 v2, 1
	v_mov_b32_e32 v4, s6
	v_mov_b32_e32 v5, 0
	v_lshl_add_u64 v[4:5], v[152:153], 0, v[4:5]
	global_atomic_add v2, v[4:5], v2, off offset:256 sc0
	s_waitcnt vmcnt(0)
	v_readfirstlane_b32 s6, v2
	s_nop 1
	s_cmp_lt_u32 s6, 0x84
	s_cbranch_scc1 .Lq_got
	s_add_u32 s8, s8, 1
	s_nop 0
	v_writelane_b32 v255, s8, 23
	s_nop 1
	s_branch .Lq_retry
.Lq_got:
	s_cmp_lt_u32 s6, 66
	s_cselect_b32 s7, 0, 1
	s_mul_i32 s8, s7, 66
	s_sub_u32 s6, s6, s8
	s_lshr_b32 s8, s6, 1
	s_and_b32 s6, s6, 1
	s_lshl_b32 s6, s6, 3
	s_add_u32 s9, s9, s6
	s_lshl_b32 s8, s8, 4
	s_add_u32 s8, s8, s9
	s_mul_i32 s7, s7, 0x210
	s_add_u32 s8, s8, s7
	v_mov_b32_e32 v0, s8
	s_branch .Lq_store
.Lq_done_all:
	v_mov_b32_e32 v0, 0x7d0
.Lq_store:
	ds_write_b32 v182, v0
